# gdn scan pass 3: nt cache policy on the once-read chunk-image LDS-DMA stream
# speedup vs baseline: 1.0175x; 1.0113x over previous
; #define SCAN_BAR() do { __builtin_amdgcn_sched_barrier(0); asm volatile("s_waitcnt lgkmcnt(0)\n\ts_barrier" ::: "memory"); __builtin_amdgcn_sched_barrier(0); } while (0)
; #define DMA_UNIT(u, slot) do { const char* src_ = (const char*)(IMGH + (size_t)(u) * 16384) + piece0 * 1024 + lane * 16; \
;         _Pragma("unroll") for (int k_ = 0; k_ < NP; ++k_) __builtin_amdgcn_global_load_lds((const unsigned*)(src_ + k_ * 1024), (LAS unsigned*)(ldsl + (slot) * 32768 + (piece0 + k_) * 1024), 16, 0, 0); } while (0)
; template <bool PASS1>
; DI void gdn_scan(const Params& P, int h, int g, unsigned char* lds, LAS unsigned char* ldsl, int tid) {
;     ...
;         DMA_UNIT(0, 0); DMA_UNIT(1, 1); DMA_UNIT(2, 2);
;         if constexpr (PASS1) asm volatile("s_waitcnt vmcnt(16)" ::: "memory"); else asm volatile("s_waitcnt vmcnt(32)" ::: "memory");
;         SCAN_BAR();
;         for (int n = 0; n < SCAN_L; ++n) {
;             const int un = n + 3 < SCAN_L ? n + 3 : SCAN_L - 1;
;             DMA_UNIT(un, (n + 3) & 3);
;             if constexpr (PASS1) asm volatile("s_waitcnt vmcnt(16)" ::: "memory"); else asm volatile("s_waitcnt vmcnt(32)" ::: "memory");
;             SCAN_BAR();
;         }
.LBB0_678:
	s_lshl_b32 s2, s0, 14
	s_lshl_b64 s[0:1], s[4:5], 15
	v_readlane_b32 s8, v239, 1
	v_readlane_b32 s9, v239, 2
	s_add_u32 s0, s8, s0
	s_addc_u32 s1, s9, s1
	s_add_u32 s0, s0, s2
	s_addc_u32 s1, s1, 0
	s_add_i32 s3, s2, 0
	v_lshl_add_u64 v[2:3], s[0:1], 0, v[108:109]
	s_mov_b32 m0, s3
	s_add_i32 s0, s3, 0x400
	global_load_lds_dwordx4 v[2:3], off nt
	v_lshl_add_u64 v[4:5], v[2:3], 0, s[14:15]
	s_mov_b32 m0, s0
	s_mov_b32 s6, s0
	s_add_i32 s0, s3, 0x800
	global_load_lds_dwordx4 v[4:5], off nt
	v_lshl_add_u64 v[4:5], v[2:3], 0, s[16:17]
	s_mov_b32 m0, s0
	s_mov_b32 s23, s0
	s_add_i32 s0, s3, 0xc00
	global_load_lds_dwordx4 v[4:5], off nt
	v_lshl_add_u64 v[4:5], v[2:3], 0, s[28:29]
	s_mov_b32 m0, s0
	s_mov_b32 s24, s0
	s_add_i32 s0, s3, 0x1000
	global_load_lds_dwordx4 v[4:5], off nt
	v_lshl_add_u64 v[4:5], v[2:3], 0, s[18:19]
	s_mov_b32 m0, s0
	s_mov_b32 s18, s0
	s_add_i32 s0, s3, 0x1400
	global_load_lds_dwordx4 v[4:5], off nt
	v_lshl_add_u64 v[4:5], v[2:3], 0, s[20:21]
	s_mov_b32 m0, s0
	s_mov_b32 s19, s0
	s_add_i32 s0, s3, 0x1800
	global_load_lds_dwordx4 v[4:5], off nt
	v_lshl_add_u64 v[4:5], v[2:3], 0, s[40:41]
	s_mov_b32 m0, s0
	s_mov_b32 s20, s0
	global_load_lds_dwordx4 v[4:5], off nt
	v_lshl_add_u64 v[4:5], v[2:3], 0, s[36:37]
	s_add_i32 s37, s3, 0x1c00
	s_mov_b32 m0, s37
	s_mov_b64 s[0:1], 0x2000
	s_add_i32 s38, s3, 0x2000
	global_load_lds_dwordx4 v[4:5], off nt
	v_lshl_add_u64 v[4:5], v[2:3], 0, s[0:1]
	s_mov_b32 m0, s38
	s_mov_b64 s[0:1], 0x2400
	s_add_i32 s39, s3, 0x2400
	global_load_lds_dwordx4 v[4:5], off nt
	v_lshl_add_u64 v[4:5], v[2:3], 0, s[0:1]
	s_mov_b32 m0, s39
	s_mov_b64 s[0:1], 0x2800
	s_add_i32 s40, s3, 0x2800
	global_load_lds_dwordx4 v[4:5], off nt
	v_lshl_add_u64 v[4:5], v[2:3], 0, s[0:1]
	s_mov_b32 m0, s40
	s_mov_b64 s[0:1], 0x2c00
	s_add_i32 s28, s3, 0x2c00
	global_load_lds_dwordx4 v[4:5], off nt
	v_lshl_add_u64 v[4:5], v[2:3], 0, s[0:1]
	s_mov_b32 m0, s28
	s_mov_b64 s[0:1], 0x3000
	s_add_i32 s29, s3, 0x3000
	global_load_lds_dwordx4 v[4:5], off nt
	v_lshl_add_u64 v[4:5], v[2:3], 0, s[0:1]
	s_mov_b32 m0, s29
	s_mov_b64 s[0:1], 0x3400
	s_add_i32 s72, s3, 0x3400
	global_load_lds_dwordx4 v[4:5], off nt
	v_lshl_add_u64 v[4:5], v[2:3], 0, s[0:1]
	s_mov_b32 m0, s72
	s_mov_b64 s[0:1], 0x3800
	s_add_i32 s73, s3, 0x3800
	global_load_lds_dwordx4 v[4:5], off nt
	v_lshl_add_u64 v[4:5], v[2:3], 0, s[0:1]
	s_mov_b32 m0, s73
	s_mov_b64 s[0:1], 0x3c00
	s_add_i32 vcc_lo, s3, 0x3c00
	global_load_lds_dwordx4 v[4:5], off nt
	v_lshl_add_u64 v[4:5], v[2:3], 0, s[0:1]
	s_mov_b32 m0, vcc_lo
	s_mov_b64 s[0:1], 0x8000
	global_load_lds_dwordx4 v[4:5], off nt
	v_lshl_add_u64 v[4:5], v[2:3], 0, s[0:1]
	s_add_i32 s0, s3, 0x8000
	s_mov_b32 m0, s0
	s_mov_b32 s21, s0
	s_mov_b64 s[0:1], 0x8400
	s_add_i32 s57, s3, 0x8400
	global_load_lds_dwordx4 v[4:5], off nt
	v_lshl_add_u64 v[4:5], v[2:3], 0, s[0:1]
	s_mov_b32 m0, s57
	s_mov_b64 s[0:1], 0x8800
	s_add_i32 s76, s3, 0x8800
	global_load_lds_dwordx4 v[4:5], off nt
	v_lshl_add_u64 v[4:5], v[2:3], 0, s[0:1]
	s_mov_b32 m0, s76
	s_mov_b64 s[0:1], 0x8c00
	s_add_i32 s77, s3, 0x8c00
	global_load_lds_dwordx4 v[4:5], off nt
	v_lshl_add_u64 v[4:5], v[2:3], 0, s[0:1]
	s_mov_b32 m0, s77
	s_mov_b64 s[8:9], 0x9000
	s_add_i32 s82, s3, 0x9000
	global_load_lds_dwordx4 v[4:5], off nt
	v_lshl_add_u64 v[4:5], v[2:3], 0, s[8:9]
	s_mov_b32 m0, s82
	s_mov_b64 s[8:9], 0x9400
	s_add_i32 s83, s3, 0x9400
	global_load_lds_dwordx4 v[4:5], off nt
	v_lshl_add_u64 v[4:5], v[2:3], 0, s[8:9]
	s_mov_b32 m0, s83
	s_mov_b64 s[8:9], 0x9800
	s_add_i32 s0, s3, 0x9800
	global_load_lds_dwordx4 v[4:5], off nt
	v_lshl_add_u64 v[4:5], v[2:3], 0, s[8:9]
	s_mov_b32 m0, s0
	s_mov_b64 s[8:9], 0x9c00
	s_add_i32 s92, s3, 0x9c00
	global_load_lds_dwordx4 v[4:5], off nt
	v_lshl_add_u64 v[4:5], v[2:3], 0, s[8:9]
	s_mov_b32 m0, s92
	s_mov_b64 s[8:9], 0xa000
	s_add_i32 s93, s3, 0xa000
	global_load_lds_dwordx4 v[4:5], off nt
	v_lshl_add_u64 v[4:5], v[2:3], 0, s[8:9]
	s_mov_b32 m0, s93
	s_mov_b64 s[8:9], 0xa400
	s_add_i32 s94, s3, 0xa400
	global_load_lds_dwordx4 v[4:5], off nt
	v_lshl_add_u64 v[4:5], v[2:3], 0, s[8:9]
	s_mov_b32 m0, s94
	s_mov_b64 s[8:9], 0xa800
	s_add_i32 s95, s3, 0xa800
	s_mov_b32 s1, s0
	global_load_lds_dwordx4 v[4:5], off nt
	v_lshl_add_u64 v[4:5], v[2:3], 0, s[8:9]
	s_mov_b32 m0, s95
	s_mov_b64 s[8:9], 0xac00
	s_add_i32 s0, s3, 0xac00
	global_load_lds_dwordx4 v[4:5], off nt
	v_lshl_add_u64 v[4:5], v[2:3], 0, s[8:9]
	s_mov_b32 m0, s0
	s_mov_b32 s25, s0
	s_mov_b64 s[8:9], 0xb000
	s_add_i32 s0, s3, 0xb000
	global_load_lds_dwordx4 v[4:5], off nt
	v_lshl_add_u64 v[4:5], v[2:3], 0, s[8:9]
	s_mov_b32 m0, s0
	s_mov_b32 s27, s0
	s_mov_b64 s[8:9], 0xb400
	s_add_i32 s0, s3, 0xb400
	v_writelane_b32 v238, s33, 11
	global_load_lds_dwordx4 v[4:5], off nt
	v_lshl_add_u64 v[4:5], v[2:3], 0, s[8:9]
	s_mov_b32 m0, s0
	s_mov_b32 s62, s0
	s_mov_b64 s[8:9], 0xb800
	s_add_i32 s0, s3, 0xb800
	global_load_lds_dwordx4 v[4:5], off nt
	v_lshl_add_u64 v[4:5], v[2:3], 0, s[8:9]
	v_writelane_b32 v238, s0, 12
	s_mov_b32 m0, s0
	s_mov_b64 s[8:9], 0xbc00
	s_add_i32 s0, s3, 0xbc00
	global_load_lds_dwordx4 v[4:5], off nt
	v_lshl_add_u64 v[4:5], v[2:3], 0, s[8:9]
	s_mov_b32 m0, s0
	s_mov_b32 s22, s0
	s_add_i32 s0, s43, s2
	s_or_b32 s4, s2, 0x400
	global_load_lds_dwordx4 v[4:5], off nt
	v_lshl_add_u64 v[4:5], v[2:3], 0, s[58:59]
	v_writelane_b32 v238, s0, 13
	s_mov_b32 m0, s0
	s_mov_b64 s[8:9], 0x10400
	s_add_i32 s0, s43, s4
	s_or_b32 s5, s2, 0x800
	global_load_lds_dwordx4 v[4:5], off nt
	v_lshl_add_u64 v[4:5], v[2:3], 0, s[8:9]
	v_writelane_b32 v238, s0, 14
	s_mov_b32 m0, s0
	s_add_i32 s0, s43, s5
	s_or_b32 s12, s2, 0xc00
	global_load_lds_dwordx4 v[4:5], off nt
; #define SCAN_BAR() do { __builtin_amdgcn_sched_barrier(0); asm volatile("s_waitcnt lgkmcnt(0)\n\ts_barrier" ::: "memory"); __builtin_amdgcn_sched_barrier(0); } while (0)
; #define DMA_UNIT(u, slot) do { const char* src_ = (const char*)(IMGH + (size_t)(u) * 16384) + piece0 * 1024 + lane * 16; \
;         _Pragma("unroll") for (int k_ = 0; k_ < NP; ++k_) __builtin_amdgcn_global_load_lds((const unsigned*)(src_ + k_ * 1024), (LAS unsigned*)(ldsl + (slot) * 32768 + (piece0 + k_) * 1024), 16, 0, 0); } while (0)
; template <bool PASS1>
; DI void gdn_scan(const Params& P, int h, int g, unsigned char* lds, LAS unsigned char* ldsl, int tid) {
;     ...
;         DMA_UNIT(0, 0); DMA_UNIT(1, 1); DMA_UNIT(2, 2);
;         if constexpr (PASS1) asm volatile("s_waitcnt vmcnt(16)" ::: "memory"); else asm volatile("s_waitcnt vmcnt(32)" ::: "memory");
;         SCAN_BAR();
;         for (int n = 0; n < SCAN_L; ++n) {
;             const int un = n + 3 < SCAN_L ? n + 3 : SCAN_L - 1;
;             DMA_UNIT(un, (n + 3) & 3);
;             if constexpr (PASS1) asm volatile("s_waitcnt vmcnt(16)" ::: "memory"); else asm volatile("s_waitcnt vmcnt(32)" ::: "memory");
;             SCAN_BAR();
;         }
	v_writelane_b32 v238, s0, 15
	s_mov_b32 m0, s0
	s_add_i32 s0, s43, s12
	s_mov_b64 s[8:9], 0x10800
	v_writelane_b32 v238, s0, 16
	v_lshl_add_u64 v[4:5], v[2:3], 0, s[8:9]
	s_mov_b64 s[8:9], 0x10c00
	v_writelane_b32 v238, s13, 17
	s_or_b32 s13, s2, 0x1000
	global_load_lds_dwordx4 v[4:5], off nt
	v_lshl_add_u64 v[4:5], v[2:3], 0, s[8:9]
	s_mov_b32 m0, s0
	s_mov_b64 s[8:9], 0x11000
	s_add_i32 s0, s43, s13
	s_or_b32 s14, s2, 0x1400
	global_load_lds_dwordx4 v[4:5], off nt
	v_lshl_add_u64 v[4:5], v[2:3], 0, s[8:9]
	v_writelane_b32 v238, s0, 18
	s_mov_b32 m0, s0
	s_mov_b64 s[8:9], 0x11400
	s_add_i32 s0, s43, s14
	s_or_b32 s15, s2, 0x1800
	global_load_lds_dwordx4 v[4:5], off nt
	v_lshl_add_u64 v[4:5], v[2:3], 0, s[8:9]
	s_mov_b32 m0, s0
	s_mov_b64 s[8:9], 0x11800
	s_add_i32 vcc_hi, s43, s15
	s_or_b32 s16, s2, 0x1c00
	global_load_lds_dwordx4 v[4:5], off nt
	v_lshl_add_u64 v[4:5], v[2:3], 0, s[8:9]
	s_mov_b32 m0, vcc_hi
	s_mov_b64 s[8:9], 0x11c00
	s_add_i32 s35, s43, s16
	s_or_b32 s17, s2, 0x2000
	global_load_lds_dwordx4 v[4:5], off nt
	v_lshl_add_u64 v[4:5], v[2:3], 0, s[8:9]
	s_mov_b32 m0, s35
	s_mov_b64 s[8:9], 0x12000
	s_add_i32 s34, s43, s17
	s_or_b32 s41, s2, 0x2400
	global_load_lds_dwordx4 v[4:5], off nt
	v_lshl_add_u64 v[4:5], v[2:3], 0, s[8:9]
	s_mov_b32 m0, s34
	s_mov_b64 s[8:9], 0x12400
	s_add_i32 s31, s43, s41
	s_or_b32 s42, s2, 0x2800
	global_load_lds_dwordx4 v[4:5], off nt
	v_lshl_add_u64 v[4:5], v[2:3], 0, s[8:9]
	s_mov_b32 m0, s31
	s_mov_b64 s[8:9], 0x12800
	s_add_i32 s30, s43, s42
	s_or_b32 s33, s2, 0x2c00
	v_readlane_b32 s11, v239, 4
	global_load_lds_dwordx4 v[4:5], off nt
	v_lshl_add_u64 v[4:5], v[2:3], 0, s[8:9]
	s_mov_b32 m0, s30
	s_mov_b64 s[8:9], 0x12c00
	s_add_i32 s26, s43, s33
	s_or_b32 s58, s2, 0x3000
	v_readlane_b32 s10, v239, 3
	global_load_lds_dwordx4 v[4:5], off nt
	v_lshl_add_u64 v[4:5], v[2:3], 0, s[8:9]
	s_mov_b32 m0, s26
	s_mov_b64 s[8:9], 0x13000
	s_add_i32 s11, s43, s58
	s_or_b32 s59, s2, 0x3400
	v_writelane_b32 v238, s0, 19
	global_load_lds_dwordx4 v[4:5], off nt
	v_lshl_add_u64 v[4:5], v[2:3], 0, s[8:9]
	s_mov_b32 m0, s11
	s_mov_b64 s[8:9], 0x13400
	s_add_i32 s10, s43, s59
	s_or_b32 s0, s2, 0x3800
	global_load_lds_dwordx4 v[4:5], off nt
	v_lshl_add_u64 v[4:5], v[2:3], 0, s[8:9]
	s_mov_b32 m0, s10
	s_mov_b64 s[8:9], 0x13800
	s_add_i32 s63, s43, s0
	s_or_b32 s44, s2, 0x3c00
	global_load_lds_dwordx4 v[4:5], off nt
	v_lshl_add_u64 v[4:5], v[2:3], 0, s[8:9]
	s_mov_b32 m0, s63
	s_mov_b64 s[8:9], 0x13c00
	s_add_i32 s64, s43, s44
	global_load_lds_dwordx4 v[4:5], off nt
	v_lshl_add_u64 v[4:5], v[2:3], 0, s[8:9]
	s_mov_b32 m0, s64
	s_nop 0
	global_load_lds_dwordx4 v[4:5], off nt
	s_waitcnt vmcnt(32)
	s_waitcnt lgkmcnt(0)
	s_barrier
	s_mov_b64 s[8:9], 0x18000
	s_add_i32 s67, s69, s2
	v_lshl_add_u64 v[4:5], v[2:3], 0, s[8:9]
	s_mov_b32 m0, s67
	s_mov_b64 s[8:9], 0x18400
	s_add_i32 s65, s69, s4
	global_load_lds_dwordx4 v[4:5], off nt
	v_lshl_add_u64 v[4:5], v[2:3], 0, s[8:9]
	s_mov_b32 m0, s65
	s_mov_b64 s[8:9], 0x18800
	s_add_i32 s66, s69, s5
	global_load_lds_dwordx4 v[4:5], off nt
	v_lshl_add_u64 v[4:5], v[2:3], 0, s[8:9]
	s_mov_b32 m0, s66
	s_mov_b64 s[8:9], 0x18c00
	s_add_i32 s74, s69, s12
	global_load_lds_dwordx4 v[4:5], off nt
	v_lshl_add_u64 v[4:5], v[2:3], 0, s[8:9]
	s_mov_b32 m0, s74
	s_mov_b64 s[8:9], 0x19000
	s_add_i32 s75, s69, s13
	global_load_lds_dwordx4 v[4:5], off nt
	v_lshl_add_u64 v[4:5], v[2:3], 0, s[8:9]
	s_mov_b32 m0, s75
	s_mov_b64 s[8:9], 0x19400
	global_load_lds_dwordx4 v[4:5], off nt
	v_lshl_add_u64 v[4:5], v[2:3], 0, s[8:9]
	s_add_i32 s9, s69, s14
	s_mov_b32 m0, s9
	s_mov_b64 s[12:13], 0x19800
	s_add_i32 s2, s69, s15
	global_load_lds_dwordx4 v[4:5], off nt
	v_lshl_add_u64 v[4:5], v[2:3], 0, s[12:13]
	s_mov_b32 m0, s2
	s_mov_b64 s[12:13], 0x19c00
	global_load_lds_dwordx4 v[4:5], off nt
	v_lshl_add_u64 v[4:5], v[2:3], 0, s[12:13]
	s_add_i32 s12, s69, s16
	s_mov_b32 m0, s12
	s_mov_b64 s[14:15], 0x1a000
	s_add_i32 s13, s69, s17
	global_load_lds_dwordx4 v[4:5], off nt
	v_lshl_add_u64 v[4:5], v[2:3], 0, s[14:15]
	s_mov_b32 m0, s13
	s_mov_b64 s[14:15], 0x1a400
	global_load_lds_dwordx4 v[4:5], off nt
	v_lshl_add_u64 v[4:5], v[2:3], 0, s[14:15]
	s_add_i32 s14, s69, s41
	s_mov_b32 m0, s14
	s_mov_b64 s[16:17], 0x1a800
	s_add_i32 s15, s69, s42
	global_load_lds_dwordx4 v[4:5], off nt
	v_lshl_add_u64 v[4:5], v[2:3], 0, s[16:17]
	s_mov_b32 m0, s15
	s_mov_b64 s[16:17], 0x1ac00
	global_load_lds_dwordx4 v[4:5], off nt
	v_lshl_add_u64 v[4:5], v[2:3], 0, s[16:17]
	s_add_i32 s16, s69, s33
	s_mov_b32 m0, s16
	s_mov_b64 s[4:5], 0x1b000
	s_add_i32 s17, s69, s58
	global_load_lds_dwordx4 v[4:5], off nt
	v_lshl_add_u64 v[4:5], v[2:3], 0, s[4:5]
	s_mov_b32 m0, s17
	s_mov_b64 s[4:5], 0x1b400
	s_add_i32 s41, s69, s59
	global_load_lds_dwordx4 v[4:5], off nt
	v_lshl_add_u64 v[4:5], v[2:3], 0, s[4:5]
	s_mov_b32 m0, s41
	s_mov_b64 s[4:5], 0x1b800
	s_add_i32 s42, s69, s0
	global_load_lds_dwordx4 v[4:5], off nt
	v_lshl_add_u64 v[4:5], v[2:3], 0, s[4:5]
	s_mov_b32 m0, s42
	s_mov_b64 s[4:5], 0x1bc00
	s_add_i32 s8, s69, s44
	global_load_lds_dwordx4 v[4:5], off nt
	v_lshl_add_u64 v[4:5], v[2:3], 0, s[4:5]
	s_mov_b32 m0, s8
	s_nop 0
	global_load_lds_dwordx4 v[4:5], off nt
	s_waitcnt vmcnt(32)
	s_waitcnt lgkmcnt(0)
	s_barrier
; #define SCAN_BAR() do { __builtin_amdgcn_sched_barrier(0); asm volatile("s_waitcnt lgkmcnt(0)\n\ts_barrier" ::: "memory"); __builtin_amdgcn_sched_barrier(0); } while (0)
; #define DMA_UNIT(u, slot) do { const char* src_ = (const char*)(IMGH + (size_t)(u) * 16384) + piece0 * 1024 + lane * 16; \
;         _Pragma("unroll") for (int k_ = 0; k_ < NP; ++k_) __builtin_amdgcn_global_load_lds((const unsigned*)(src_ + k_ * 1024), (LAS unsigned*)(ldsl + (slot) * 32768 + (piece0 + k_) * 1024), 16, 0, 0); } while (0)
; template <bool PASS1>
; DI void gdn_scan(const Params& P, int h, int g, unsigned char* lds, LAS unsigned char* ldsl, int tid) {
;     ...
;         for (int n = 0; n < SCAN_L; ++n) {
;             const int un = n + 3 < SCAN_L ? n + 3 : SCAN_L - 1;
;             DMA_UNIT(un, (n + 3) & 3);
;             if constexpr (PASS1) asm volatile("s_waitcnt vmcnt(16)" ::: "memory"); else asm volatile("s_waitcnt vmcnt(32)" ::: "memory");
;             SCAN_BAR();
;         }
	s_mov_b64 s[4:5], 0x20000
	s_mov_b32 m0, s3
	v_lshl_add_u64 v[4:5], v[2:3], 0, s[4:5]
	s_mov_b64 s[4:5], 0x20400
	global_load_lds_dwordx4 v[4:5], off nt
	v_lshl_add_u64 v[4:5], v[2:3], 0, s[4:5]
	s_mov_b32 m0, s6
	s_mov_b64 s[4:5], 0x20800
	global_load_lds_dwordx4 v[4:5], off nt
	v_lshl_add_u64 v[4:5], v[2:3], 0, s[4:5]
	s_mov_b32 m0, s23
	s_mov_b64 s[4:5], 0x20c00
	global_load_lds_dwordx4 v[4:5], off nt
	v_lshl_add_u64 v[4:5], v[2:3], 0, s[4:5]
	s_mov_b32 m0, s24
	s_mov_b64 s[4:5], 0x21000
	global_load_lds_dwordx4 v[4:5], off nt
	v_lshl_add_u64 v[4:5], v[2:3], 0, s[4:5]
	s_mov_b32 m0, s18
	s_mov_b64 s[4:5], 0x21400
	global_load_lds_dwordx4 v[4:5], off nt
	v_lshl_add_u64 v[4:5], v[2:3], 0, s[4:5]
	s_mov_b32 m0, s19
	s_mov_b64 s[4:5], 0x21800
	global_load_lds_dwordx4 v[4:5], off nt
	v_lshl_add_u64 v[4:5], v[2:3], 0, s[4:5]
	s_mov_b32 m0, s20
	s_mov_b64 s[4:5], 0x21c00
	global_load_lds_dwordx4 v[4:5], off nt
	v_lshl_add_u64 v[4:5], v[2:3], 0, s[4:5]
	s_mov_b32 m0, s37
	s_mov_b64 s[4:5], 0x22000
	global_load_lds_dwordx4 v[4:5], off nt
	v_lshl_add_u64 v[4:5], v[2:3], 0, s[4:5]
	s_mov_b32 m0, s38
	s_mov_b64 s[4:5], 0x22400
	global_load_lds_dwordx4 v[4:5], off nt
	v_lshl_add_u64 v[4:5], v[2:3], 0, s[4:5]
	s_mov_b32 m0, s39
	s_mov_b64 s[4:5], 0x22800
	global_load_lds_dwordx4 v[4:5], off nt
	v_lshl_add_u64 v[4:5], v[2:3], 0, s[4:5]
	s_mov_b32 m0, s40
	s_mov_b64 s[4:5], 0x22c00
	global_load_lds_dwordx4 v[4:5], off nt
	v_lshl_add_u64 v[4:5], v[2:3], 0, s[4:5]
	s_mov_b32 m0, s28
	s_mov_b64 s[4:5], 0x23000
	global_load_lds_dwordx4 v[4:5], off nt
	v_lshl_add_u64 v[4:5], v[2:3], 0, s[4:5]
	s_mov_b32 m0, s29
	s_mov_b64 s[4:5], 0x23400
	global_load_lds_dwordx4 v[4:5], off nt
	v_lshl_add_u64 v[4:5], v[2:3], 0, s[4:5]
	s_mov_b32 m0, s72
	s_mov_b64 s[4:5], 0x23800
	global_load_lds_dwordx4 v[4:5], off nt
	v_lshl_add_u64 v[4:5], v[2:3], 0, s[4:5]
	s_mov_b32 m0, s73
	s_mov_b64 s[4:5], 0x23c00
	global_load_lds_dwordx4 v[4:5], off nt
	v_lshl_add_u64 v[4:5], v[2:3], 0, s[4:5]
	s_mov_b32 m0, vcc_lo
	s_mov_b32 s33, s23
	global_load_lds_dwordx4 v[4:5], off nt
	s_waitcnt vmcnt(32)
	s_mov_b32 s58, s18
	s_mov_b32 s59, s19
	s_mov_b32 s36, s20
	s_mov_b32 s0, s6
	s_mov_b32 s44, s24
	s_waitcnt lgkmcnt(0)
	s_barrier
	s_mov_b64 s[4:5], 0x28000
	s_mov_b32 m0, s21
	v_lshl_add_u64 v[4:5], v[2:3], 0, s[4:5]
	s_mov_b64 s[4:5], 0x28400
	global_load_lds_dwordx4 v[4:5], off nt
	v_lshl_add_u64 v[4:5], v[2:3], 0, s[4:5]
	s_mov_b32 m0, s57
	s_mov_b64 s[4:5], 0x28800
	global_load_lds_dwordx4 v[4:5], off nt
	v_lshl_add_u64 v[4:5], v[2:3], 0, s[4:5]
	s_mov_b32 m0, s76
	s_mov_b64 s[4:5], 0x28c00
	global_load_lds_dwordx4 v[4:5], off nt
	v_lshl_add_u64 v[4:5], v[2:3], 0, s[4:5]
	s_mov_b32 m0, s77
	s_mov_b64 s[4:5], 0x29000
	global_load_lds_dwordx4 v[4:5], off nt
	v_lshl_add_u64 v[4:5], v[2:3], 0, s[4:5]
	s_mov_b32 m0, s82
	s_mov_b64 s[4:5], 0x29400
	global_load_lds_dwordx4 v[4:5], off nt
	v_lshl_add_u64 v[4:5], v[2:3], 0, s[4:5]
	s_mov_b32 m0, s83
	s_mov_b64 s[4:5], 0x29800
	global_load_lds_dwordx4 v[4:5], off nt
	v_lshl_add_u64 v[4:5], v[2:3], 0, s[4:5]
	s_mov_b32 m0, s1
	s_mov_b64 s[4:5], 0x29c00
	global_load_lds_dwordx4 v[4:5], off nt
	v_lshl_add_u64 v[4:5], v[2:3], 0, s[4:5]
	s_mov_b32 m0, s92
	s_mov_b64 s[4:5], 0x2a000
	global_load_lds_dwordx4 v[4:5], off nt
	v_lshl_add_u64 v[4:5], v[2:3], 0, s[4:5]
	s_mov_b32 m0, s93
	s_mov_b64 s[4:5], 0x2a400
	global_load_lds_dwordx4 v[4:5], off nt
	v_lshl_add_u64 v[4:5], v[2:3], 0, s[4:5]
	s_mov_b32 m0, s94
	s_mov_b64 s[4:5], 0x2a800
	global_load_lds_dwordx4 v[4:5], off nt
	v_lshl_add_u64 v[4:5], v[2:3], 0, s[4:5]
	s_mov_b32 m0, s95
	s_mov_b64 s[4:5], 0x2ac00
	global_load_lds_dwordx4 v[4:5], off nt
	v_lshl_add_u64 v[4:5], v[2:3], 0, s[4:5]
	s_mov_b32 m0, s25
	s_mov_b64 s[4:5], 0x2b000
	global_load_lds_dwordx4 v[4:5], off nt
	v_lshl_add_u64 v[4:5], v[2:3], 0, s[4:5]
	s_mov_b32 m0, s27
	s_mov_b64 s[4:5], 0x2b400
	s_mov_b32 s56, s21
	global_load_lds_dwordx4 v[4:5], off nt
	v_lshl_add_u64 v[4:5], v[2:3], 0, s[4:5]
	s_mov_b32 m0, s62
	s_mov_b64 s[4:5], 0x2b800
	v_readlane_b32 s21, v238, 12
	global_load_lds_dwordx4 v[4:5], off nt
	v_lshl_add_u64 v[4:5], v[2:3], 0, s[4:5]
	s_mov_b32 m0, s21
	s_mov_b64 s[4:5], 0x2bc00
	global_load_lds_dwordx4 v[4:5], off nt
	v_lshl_add_u64 v[4:5], v[2:3], 0, s[4:5]
	s_mov_b32 m0, s22
	s_mov_b32 s18, s25
	global_load_lds_dwordx4 v[4:5], off nt
	s_waitcnt vmcnt(32)
	s_mov_b32 s19, s27
	s_mov_b32 s20, s62
	s_mov_b32 s6, s1
	s_mov_b32 s1, s22
	s_waitcnt lgkmcnt(0)
	s_barrier
	v_readlane_b32 s22, v238, 13
	s_mov_b64 s[4:5], 0x30000
	s_mov_b32 m0, s22
	v_lshl_add_u64 v[4:5], v[2:3], 0, s[4:5]
	s_mov_b64 s[4:5], 0x30400
	v_readlane_b32 s23, v238, 14
	global_load_lds_dwordx4 v[4:5], off nt
	v_lshl_add_u64 v[4:5], v[2:3], 0, s[4:5]
	s_mov_b32 m0, s23
	s_mov_b64 s[4:5], 0x30800
	v_readlane_b32 s27, v238, 15
	global_load_lds_dwordx4 v[4:5], off nt
	v_lshl_add_u64 v[4:5], v[2:3], 0, s[4:5]
	s_mov_b32 m0, s27
	s_mov_b64 s[4:5], 0x30c00
	v_readlane_b32 s24, v238, 16
	global_load_lds_dwordx4 v[4:5], off nt
	v_lshl_add_u64 v[4:5], v[2:3], 0, s[4:5]
	s_mov_b32 m0, s24
	s_mov_b64 s[4:5], 0x31000
	v_readlane_b32 s25, v238, 18
	global_load_lds_dwordx4 v[4:5], off nt
	v_lshl_add_u64 v[4:5], v[2:3], 0, s[4:5]
	s_mov_b32 m0, s25
	s_mov_b64 s[4:5], 0x31400
	v_readlane_b32 s62, v238, 19
	global_load_lds_dwordx4 v[4:5], off nt
	v_lshl_add_u64 v[4:5], v[2:3], 0, s[4:5]
	s_mov_b32 m0, s62
	s_mov_b64 s[4:5], 0x31800
	global_load_lds_dwordx4 v[4:5], off nt
	v_lshl_add_u64 v[4:5], v[2:3], 0, s[4:5]
	s_mov_b32 m0, vcc_hi
	s_mov_b64 s[4:5], 0x31c00
	global_load_lds_dwordx4 v[4:5], off nt
	v_lshl_add_u64 v[4:5], v[2:3], 0, s[4:5]
	s_mov_b32 m0, s35
	s_mov_b64 s[4:5], 0x32000
	global_load_lds_dwordx4 v[4:5], off nt
	v_lshl_add_u64 v[4:5], v[2:3], 0, s[4:5]
	s_mov_b32 m0, s34
	s_mov_b64 s[4:5], 0x32400
	global_load_lds_dwordx4 v[4:5], off nt
	v_lshl_add_u64 v[4:5], v[2:3], 0, s[4:5]
	s_mov_b32 m0, s31
	s_mov_b64 s[4:5], 0x32800
	global_load_lds_dwordx4 v[4:5], off nt
	v_lshl_add_u64 v[4:5], v[2:3], 0, s[4:5]
	s_mov_b32 m0, s30
	s_mov_b64 s[4:5], 0x32c00
	global_load_lds_dwordx4 v[4:5], off nt
	v_lshl_add_u64 v[4:5], v[2:3], 0, s[4:5]
	s_mov_b32 m0, s26
	s_mov_b64 s[4:5], 0x33000
	global_load_lds_dwordx4 v[4:5], off nt
	v_lshl_add_u64 v[4:5], v[2:3], 0, s[4:5]
	s_mov_b32 m0, s11
	s_mov_b64 s[4:5], 0x33400
	global_load_lds_dwordx4 v[4:5], off nt
	v_lshl_add_u64 v[4:5], v[2:3], 0, s[4:5]
	s_mov_b32 m0, s10
	s_mov_b64 s[4:5], 0x33800
	global_load_lds_dwordx4 v[4:5], off nt
	v_lshl_add_u64 v[4:5], v[2:3], 0, s[4:5]
	s_mov_b32 m0, s63
	s_mov_b64 s[4:5], 0x33c00
	global_load_lds_dwordx4 v[4:5], off nt
	v_lshl_add_u64 v[4:5], v[2:3], 0, s[4:5]
	s_mov_b32 m0, s64
	s_nop 0
	global_load_lds_dwordx4 v[4:5], off nt
	s_waitcnt vmcnt(32)
	s_waitcnt lgkmcnt(0)
	s_barrier
; #define SCAN_BAR() do { __builtin_amdgcn_sched_barrier(0); asm volatile("s_waitcnt lgkmcnt(0)\n\ts_barrier" ::: "memory"); __builtin_amdgcn_sched_barrier(0); } while (0)
; #define DMA_UNIT(u, slot) do { const char* src_ = (const char*)(IMGH + (size_t)(u) * 16384) + piece0 * 1024 + lane * 16; \
;         _Pragma("unroll") for (int k_ = 0; k_ < NP; ++k_) __builtin_amdgcn_global_load_lds((const unsigned*)(src_ + k_ * 1024), (LAS unsigned*)(ldsl + (slot) * 32768 + (piece0 + k_) * 1024), 16, 0, 0); } while (0)
; template <bool PASS1>
; DI void gdn_scan(const Params& P, int h, int g, unsigned char* lds, LAS unsigned char* ldsl, int tid) {
;     ...
;         for (int n = 0; n < SCAN_L; ++n) {
;             const int un = n + 3 < SCAN_L ? n + 3 : SCAN_L - 1;
;             DMA_UNIT(un, (n + 3) & 3);
;             if constexpr (PASS1) asm volatile("s_waitcnt vmcnt(16)" ::: "memory"); else asm volatile("s_waitcnt vmcnt(32)" ::: "memory");
;             SCAN_BAR();
;         }
;         asm volatile("s_waitcnt vmcnt(0)" ::: "memory");
	s_mov_b64 s[4:5], 0x38000
	s_mov_b32 m0, s67
	v_lshl_add_u64 v[4:5], v[2:3], 0, s[4:5]
	s_mov_b64 s[4:5], 0x38400
	global_load_lds_dwordx4 v[4:5], off nt
	v_lshl_add_u64 v[6:7], v[2:3], 0, s[4:5]
	s_mov_b32 m0, s65
	s_mov_b64 s[4:5], 0x38800
	global_load_lds_dwordx4 v[6:7], off nt
	v_lshl_add_u64 v[8:9], v[2:3], 0, s[4:5]
	s_mov_b32 m0, s66
	s_mov_b64 s[4:5], 0x38c00
	global_load_lds_dwordx4 v[8:9], off nt
	v_lshl_add_u64 v[10:11], v[2:3], 0, s[4:5]
	s_mov_b32 m0, s74
	s_mov_b64 s[4:5], 0x39000
	global_load_lds_dwordx4 v[10:11], off nt
	v_lshl_add_u64 v[12:13], v[2:3], 0, s[4:5]
	s_mov_b32 m0, s75
	s_mov_b64 s[4:5], 0x39400
	global_load_lds_dwordx4 v[12:13], off nt
	v_lshl_add_u64 v[14:15], v[2:3], 0, s[4:5]
	s_mov_b32 m0, s9
	s_mov_b64 s[4:5], 0x39800
	global_load_lds_dwordx4 v[14:15], off nt
	v_lshl_add_u64 v[16:17], v[2:3], 0, s[4:5]
	s_mov_b32 m0, s2
	s_mov_b64 s[4:5], 0x39c00
	global_load_lds_dwordx4 v[16:17], off nt
	s_waitcnt vmcnt(0)
	v_lshl_add_u64 v[18:19], v[2:3], 0, s[4:5]
	s_mov_b32 m0, s12
	s_mov_b64 s[4:5], 0x3a000
	global_load_lds_dwordx4 v[18:19], off nt
	v_lshl_add_u64 v[20:21], v[2:3], 0, s[4:5]
	s_mov_b32 m0, s13
	s_mov_b64 s[4:5], 0x3a400
	global_load_lds_dwordx4 v[20:21], off nt
	v_lshl_add_u64 v[22:23], v[2:3], 0, s[4:5]
	s_mov_b32 m0, s14
	s_mov_b64 s[4:5], 0x3a800
	global_load_lds_dwordx4 v[22:23], off nt
	v_lshl_add_u64 v[24:25], v[2:3], 0, s[4:5]
	s_mov_b32 m0, s15
	s_mov_b64 s[4:5], 0x3ac00
	global_load_lds_dwordx4 v[24:25], off nt
	v_lshl_add_u64 v[26:27], v[2:3], 0, s[4:5]
	s_mov_b32 m0, s16
	s_mov_b64 s[4:5], 0x3b000
	global_load_lds_dwordx4 v[26:27], off nt
	v_lshl_add_u64 v[28:29], v[2:3], 0, s[4:5]
	s_mov_b32 m0, s17
	s_mov_b64 s[4:5], 0x3b400
	global_load_lds_dwordx4 v[28:29], off nt
	v_lshl_add_u64 v[30:31], v[2:3], 0, s[4:5]
	s_mov_b32 m0, s41
	s_mov_b64 s[4:5], 0x3b800
	global_load_lds_dwordx4 v[30:31], off nt
	v_lshl_add_u64 v[32:33], v[2:3], 0, s[4:5]
	s_mov_b32 m0, s42
	s_mov_b64 s[4:5], 0x3bc00
	global_load_lds_dwordx4 v[32:33], off nt
	v_lshl_add_u64 v[2:3], v[2:3], 0, s[4:5]
	s_mov_b32 m0, s8
	v_readlane_b32 s13, v238, 17
	global_load_lds_dwordx4 v[2:3], off nt
	s_waitcnt vmcnt(32)
	s_mov_b64 s[14:15], 0x400
	s_mov_b64 s[16:17], 0x800
	s_waitcnt lgkmcnt(0)
	s_barrier
	s_mov_b32 m0, s3
	s_nop 0
	global_load_lds_dwordx4 v[4:5], off nt
	s_mov_b32 m0, s0
	s_nop 0
	global_load_lds_dwordx4 v[6:7], off nt
	s_mov_b32 m0, s33
	s_nop 0
	global_load_lds_dwordx4 v[8:9], off nt
	s_mov_b32 m0, s44
	s_nop 0
	global_load_lds_dwordx4 v[10:11], off nt
	s_mov_b32 m0, s58
	s_nop 0
	global_load_lds_dwordx4 v[12:13], off nt
	s_mov_b32 m0, s59
	s_nop 0
	global_load_lds_dwordx4 v[14:15], off nt
	s_mov_b32 m0, s36
	s_nop 0
	global_load_lds_dwordx4 v[16:17], off nt
	s_mov_b32 m0, s37
	s_nop 0
	global_load_lds_dwordx4 v[18:19], off nt
	s_mov_b32 m0, s38
	s_nop 0
	global_load_lds_dwordx4 v[20:21], off nt
	s_mov_b32 m0, s39
	s_mov_b64 s[38:39], 0x20000
	global_load_lds_dwordx4 v[22:23], off nt
	s_mov_b32 m0, s40
	s_nop 0
	global_load_lds_dwordx4 v[24:25], off nt
	s_mov_b32 m0, s28
	s_nop 0
	global_load_lds_dwordx4 v[26:27], off nt
	s_mov_b32 m0, s29
	s_nop 0
	global_load_lds_dwordx4 v[28:29], off nt
	s_mov_b32 m0, s72
	s_nop 0
	global_load_lds_dwordx4 v[30:31], off nt
	s_mov_b32 m0, s73
	s_nop 0
	global_load_lds_dwordx4 v[32:33], off nt
	s_mov_b32 m0, vcc_lo
	s_nop 0
	global_load_lds_dwordx4 v[2:3], off nt
	s_waitcnt vmcnt(32)
	s_waitcnt lgkmcnt(0)
	s_barrier
	s_mov_b32 m0, s56
	s_mov_b64 s[36:37], 0x1c00
	global_load_lds_dwordx4 v[4:5], off nt
	s_mov_b32 m0, s57
	v_readlane_b32 s33, v238, 11
	global_load_lds_dwordx4 v[6:7], off nt
	s_mov_b32 m0, s76
	s_mov_b64 s[40:41], 0x1800
	global_load_lds_dwordx4 v[8:9], off nt
	s_mov_b32 m0, s77
	s_nop 0
	global_load_lds_dwordx4 v[10:11], off nt
	s_mov_b32 m0, s82
	s_nop 0
	global_load_lds_dwordx4 v[12:13], off nt
	s_mov_b32 m0, s83
	s_nop 0
	global_load_lds_dwordx4 v[14:15], off nt
	s_mov_b32 m0, s6
	s_nop 0
	global_load_lds_dwordx4 v[16:17], off nt
	s_mov_b32 m0, s92
	s_nop 0
	global_load_lds_dwordx4 v[18:19], off nt
	s_mov_b32 m0, s93
	s_nop 0
	global_load_lds_dwordx4 v[20:21], off nt
	s_mov_b32 m0, s94
	s_nop 0
	global_load_lds_dwordx4 v[22:23], off nt
	s_mov_b32 m0, s95
	s_nop 0
	global_load_lds_dwordx4 v[24:25], off nt
	s_mov_b32 m0, s18
	s_nop 0
	global_load_lds_dwordx4 v[26:27], off nt
	s_mov_b32 m0, s19
	s_nop 0
	global_load_lds_dwordx4 v[28:29], off nt
	s_mov_b32 m0, s20
	s_nop 0
	global_load_lds_dwordx4 v[30:31], off nt
	s_mov_b32 m0, s21
	s_nop 0
	global_load_lds_dwordx4 v[32:33], off nt
	s_mov_b32 m0, s1
	s_nop 0
	global_load_lds_dwordx4 v[2:3], off nt
	s_waitcnt vmcnt(32)
	s_waitcnt lgkmcnt(0)
	s_barrier
	s_mov_b32 m0, s22
	s_mov_b64 s[28:29], 0xc00
	global_load_lds_dwordx4 v[4:5], off nt
	s_mov_b32 m0, s23
	s_mov_b64 s[18:19], 0x1000
	global_load_lds_dwordx4 v[6:7], off nt
	s_mov_b32 m0, s27
	s_mov_b64 s[20:21], 0x1400
	global_load_lds_dwordx4 v[8:9], off nt
	s_mov_b32 m0, s24
	s_mov_b64 s[58:59], 0x10000
	global_load_lds_dwordx4 v[10:11], off nt
	s_mov_b32 m0, s25
	s_nop 0
	global_load_lds_dwordx4 v[12:13], off nt
	s_mov_b32 m0, s62
	s_nop 0
	global_load_lds_dwordx4 v[14:15], off nt
	s_mov_b32 m0, vcc_hi
	s_nop 0
	global_load_lds_dwordx4 v[16:17], off nt
	s_mov_b32 m0, s35
	s_nop 0
	global_load_lds_dwordx4 v[18:19], off nt
	s_mov_b32 m0, s34
	s_nop 0
	global_load_lds_dwordx4 v[20:21], off nt
	s_mov_b32 m0, s31
	s_nop 0
	global_load_lds_dwordx4 v[22:23], off nt
	s_mov_b32 m0, s30
	s_nop 0
	global_load_lds_dwordx4 v[24:25], off nt
	s_mov_b32 m0, s26
	s_nop 0
	global_load_lds_dwordx4 v[26:27], off nt
	s_mov_b32 m0, s11
	s_nop 0
	global_load_lds_dwordx4 v[28:29], off nt
	s_mov_b32 m0, s10
	s_nop 0
	global_load_lds_dwordx4 v[30:31], off nt
	s_mov_b32 m0, s63
	s_nop 0
	global_load_lds_dwordx4 v[32:33], off nt
	s_mov_b32 m0, s64
	s_nop 0
	global_load_lds_dwordx4 v[2:3], off nt
	s_waitcnt vmcnt(32)
	s_waitcnt lgkmcnt(0)
	s_barrier
	s_waitcnt vmcnt(0)
	v_readlane_b32 s66, v239, 58
	v_readlane_b32 s67, v239, 59
	s_mov_b32 s26, 0x20000
	s_mov_b32 s10, 0x10000
	v_readlane_b32 s11, v239, 34
	v_readlane_b32 s12, v238, 10
	s_mov_b64 s[4:5], 0
